# fox attention loop tail: pending P.V block with 6-deep pipelined fragment reads (on top of v17)
# baseline (speedup 1.0000x reference)
.LBB0_697:
	s_andn2_b64 vcc, exec, s[70:71]
	s_cbranch_vccnz .LBB0_699
	s_mul_i32 s21, s73, 0x4800
	v_add_u32_e32 v0, s21, v162
	ds_read_b128 v[206:209], v0 offset:43520
	ds_read_b128 v[210:213], v0 offset:43552
	ds_read_b128 v[214:217], v0 offset:43584
	ds_read_b128 v[218:221], v0 offset:43616
	ds_read_b128 v[222:225], v0 offset:48128
	ds_read_b128 v[226:229], v0 offset:48160
	s_waitcnt lgkmcnt(5)
	v_mfma_f32_32x32x16_bf16 v[64:79], v[206:209], v[80:83], v[64:79]
	ds_read_b128 v[206:209], v0 offset:48192
	s_waitcnt lgkmcnt(5)
	v_mfma_f32_32x32x16_bf16 v[64:79], v[210:213], v[84:87], v[64:79]
	ds_read_b128 v[210:213], v0 offset:48224
	s_waitcnt lgkmcnt(5)
	v_mfma_f32_32x32x16_bf16 v[64:79], v[214:217], v[88:91], v[64:79]
	ds_read_b128 v[214:217], v0 offset:52736
	s_waitcnt lgkmcnt(5)
	v_mfma_f32_32x32x16_bf16 v[64:79], v[218:221], v[92:95], v[64:79]
	ds_read_b128 v[218:221], v0 offset:52768
	s_waitcnt lgkmcnt(5)
	v_mfma_f32_32x32x16_bf16 v[48:63], v[222:225], v[80:83], v[48:63]
	ds_read_b128 v[222:225], v0 offset:52800
	s_waitcnt lgkmcnt(5)
	v_mfma_f32_32x32x16_bf16 v[48:63], v[226:229], v[84:87], v[48:63]
	ds_read_b128 v[226:229], v0 offset:52832
	s_waitcnt lgkmcnt(5)
	v_mfma_f32_32x32x16_bf16 v[48:63], v[206:209], v[88:91], v[48:63]
	ds_read_b128 v[206:209], v0 offset:57344
	s_waitcnt lgkmcnt(5)
	v_mfma_f32_32x32x16_bf16 v[48:63], v[210:213], v[92:95], v[48:63]
	ds_read_b128 v[210:213], v0 offset:57376
	s_waitcnt lgkmcnt(5)
	v_mfma_f32_32x32x16_bf16 v[32:47], v[214:217], v[80:83], v[32:47]
	ds_read_b128 v[214:217], v0 offset:57408
	s_waitcnt lgkmcnt(5)
	v_mfma_f32_32x32x16_bf16 v[32:47], v[218:221], v[84:87], v[32:47]
	ds_read_b128 v[218:221], v0 offset:57440
	s_waitcnt lgkmcnt(5)
	v_mfma_f32_32x32x16_bf16 v[32:47], v[222:225], v[88:91], v[32:47]
	s_waitcnt lgkmcnt(4)
	v_mfma_f32_32x32x16_bf16 v[32:47], v[226:229], v[92:95], v[32:47]
	s_waitcnt lgkmcnt(3)
	v_mfma_f32_32x32x16_bf16 v[16:31], v[206:209], v[80:83], v[16:31]
	s_waitcnt lgkmcnt(2)
	v_mfma_f32_32x32x16_bf16 v[16:31], v[210:213], v[84:87], v[16:31]
	s_waitcnt lgkmcnt(1)
	v_mfma_f32_32x32x16_bf16 v[16:31], v[214:217], v[88:91], v[16:31]
	s_waitcnt lgkmcnt(0)
	v_mfma_f32_32x32x16_bf16 v[16:31], v[218:221], v[92:95], v[16:31]
